# att24 = att14 + attention unit schedule regrouped for K/V L2 locality: 16 CUs of an XCD per (b,h), each XCD streams 2 heads at a time instead of 4 (CU j: (A,j),(A,31-j),(B,j),(B,31-j))
# speedup vs baseline: 1.0010x; 1.0010x over previous
.LBB0_278:
	v_and_b32_e32 v0, 63, v244
	v_lshlrev_b32_e32 v0, 2, v0
	global_load_dword v2, v0, s[72:73]
	global_load_dword v3, v0, s[74:75]
	global_load_dword v4, v0, s[76:77]
	s_nop 0
	global_load_dword v0, v0, s[78:79]
	v_mbcnt_hi_u32_b32 v5, -1, v145
	v_and_b32_e32 v6, 64, v5
	v_xor_b32_e32 v7, 1, v5
	v_add_u32_e32 v6, 64, v6
	v_cmp_lt_i32_e32 vcc, v7, v6
	v_xor_b32_e32 v8, 2, v5
	v_xor_b32_e32 v9, 4, v5
	v_cndmask_b32_e32 v7, v5, v7, vcc
	v_lshlrev_b32_e32 v232, 2, v7
	v_cmp_lt_i32_e32 vcc, v8, v6
	v_xor_b32_e32 v10, 8, v5
	v_xor_b32_e32 v11, 16, v5
	v_cndmask_b32_e32 v8, v5, v8, vcc
	v_lshlrev_b32_e32 v8, 2, v8
	v_cmp_lt_i32_e32 vcc, v9, v6
	v_xor_b32_e32 v12, 32, v5
	s_add_u32 s94, s22, 0xb000000
	v_cndmask_b32_e32 v9, v5, v9, vcc
	v_cmp_lt_i32_e32 vcc, v10, v6
	s_addc_u32 s95, s23, 0
	s_add_u32 s0, s22, 0xf000000
	v_cndmask_b32_e32 v10, v5, v10, vcc
	v_cmp_lt_i32_e32 vcc, v11, v6
	s_addc_u32 s1, s23, 0
	v_writelane_b32 v254, s0, 35
	s_mov_b32 s7, 0
	v_mov_b32_e32 v1, 0
	v_writelane_b32 v254, s1, 36
	s_add_u32 s0, s22, 0x13000000
	s_addc_u32 s1, s23, 0
	s_add_u32 s86, s20, 0x4000000
	v_writelane_b32 v254, s0, 37
	s_addc_u32 s87, s21, 0
	s_cmpk_lg_i32 s84, 0x100
	v_writelane_b32 v254, s1, 38
	s_cselect_b64 s[96:97], -1, 0
	s_and_b32 s0, s2, 15
	v_writelane_b32 v254, s2, 39
	s_ashr_i32 s1, s2, 3
	v_writelane_b32 v254, s1, 40
	s_ashr_i32 s1, s2, 4
	s_lshl_b32 s1, s1, 1
	v_writelane_b32 v254, s1, 48
	s_or_b32 s1, s1, 1
	v_writelane_b32 v254, s1, 49
	s_xor_b32 s1, s0, 31
	v_writelane_b32 v254, s1, 41
	s_mov_b32 s1, s0
	v_writelane_b32 v254, s1, 42
	v_writelane_b32 v254, s0, 43
	s_xor_b32 s0, s0, 31
	v_writelane_b32 v254, s0, 44
	v_writelane_b32 v254, s16, 45
	s_mov_b64 s[8:9], 0x20000
	s_mov_b64 s[10:11], 0x40000
	s_mov_b64 s[12:13], 0x60000
	s_mov_b64 s[14:15], 0x80000
	s_mov_b64 s[42:43], 0x13040000
	s_mov_b64 s[48:49], 0x13040080
	s_mov_b32 s25, 0x41000000
	v_mov_b32_e32 v230, 0x3727c5ac
	v_mov_b32_e32 v231, 0xff800000
	s_mov_b32 s27, 0
	v_writelane_b32 v254, s40, 46
	s_waitcnt vmcnt(2)
	v_mul_f32_e32 v7, v2, v3
	ds_bpermute_b32 v7, v232, v7
	s_waitcnt vmcnt(0)
	v_mul_f32_e32 v13, v4, v0
	ds_bpermute_b32 v13, v232, v13
	v_writelane_b32 v254, s41, 47
	s_waitcnt lgkmcnt(1)
	v_fmac_f32_e32 v7, v2, v3
	v_cndmask_b32_e32 v3, v5, v11, vcc
	s_waitcnt lgkmcnt(0)
	v_fmac_f32_e32 v13, v4, v0
	ds_bpermute_b32 v0, v8, v7
	ds_bpermute_b32 v2, v8, v13
	v_lshlrev_b32_e32 v4, 2, v9
	v_cmp_lt_i32_e32 vcc, v12, v6
	v_lshlrev_b32_e32 v6, 2, v10
	s_waitcnt lgkmcnt(1)
	v_add_f32_e32 v0, v7, v0
	s_waitcnt lgkmcnt(0)
	v_add_f32_e32 v2, v13, v2
	ds_bpermute_b32 v7, v4, v0
	ds_bpermute_b32 v4, v4, v2
	v_lshlrev_b32_e32 v245, 2, v3
	v_cndmask_b32_e32 v5, v5, v12, vcc
	v_lshlrev_b32_e32 v246, 2, v5
	s_waitcnt lgkmcnt(1)
	v_add_f32_e32 v0, v0, v7
	s_waitcnt lgkmcnt(0)
	v_add_f32_e32 v2, v2, v4
	ds_bpermute_b32 v4, v6, v0
	ds_bpermute_b32 v6, v6, v2
	s_waitcnt lgkmcnt(1)
	v_add_f32_e32 v0, v0, v4
	s_waitcnt lgkmcnt(0)
	v_add_f32_e32 v2, v2, v6
	ds_bpermute_b32 v3, v245, v0
	ds_bpermute_b32 v4, v245, v2
	s_waitcnt lgkmcnt(1)
	v_add_f32_e32 v0, v0, v3
	s_waitcnt lgkmcnt(0)
	v_add_f32_e32 v2, v2, v4
	ds_bpermute_b32 v3, v246, v0
	ds_bpermute_b32 v4, v246, v2
	s_waitcnt lgkmcnt(1)
	v_add_f32_e32 v0, v0, v3
	s_waitcnt lgkmcnt(0)
	v_add_f32_e32 v2, v2, v4
	v_mul_f32_e32 v0, 0x3fb8aa3b, v0
	v_mul_f32_e32 v2, 0x3fb8aa3b, v2
	v_exp_f32_e32 v0, v0
	v_exp_f32_e32 v2, v2
	s_nop 0
	v_sub_f32_e32 v0, v0, v2
	v_add_f32_e32 v233, 0x3e4ccccd, v0
	s_branch .LBB0_281

.LBB0_292:
	s_mov_b64 s[0:1], -1
	v_readlane_b32 s5, v254, 48
	s_cmp_lt_u32 s27, 2
	s_cbranch_scc1 .Lbh_a
	v_readlane_b32 s5, v254, 49
.Lbh_a:
.LBB0_293:
	s_mov_b32 s30, s4
	s_mov_b32 s33, s5
	s_andn2_b64 vcc, exec, s[0:1]
	s_mov_b64 s[0:1], -1
	s_cbranch_vccnz .LBB0_280
